# top-k bisection: packed 16-bit integer counting (v_pk_sub/min/add_u16 on key high halves) for the upper 16 bit steps
# speedup vs baseline: 1.0143x; 1.0143x over previous
; __device__ __forceinline__ void attn_item(const Ptrs& P, unsigned char* lds, int b, int tq0, int tid) {
;     ...
;             const unsigned cand = th | (1u << bit); unsigned cnt = 0, oth;
; #pragma unroll
;             for (int k = 0; k < 4; ++k) if (16 * k < nact) {
; #pragma unroll
;                 for (int r = 16 * k; r < 16 * k + 16; ++r) cnt += (unsigned)__popcll(__ballot(k2[r] >= cand)); }
.Lbis_mspin:
	ds_read_b32 v27, v37
	s_waitcnt lgkmcnt(0)
	v_readfirstlane_b32 s13, v27
	s_nop 3
	s_and_b32 s89, s13, 0xffff
	s_cmp_eq_u32 s89, s12
	s_cbranch_scc0 .Lbis_mspin
	s_lshr_b32 s13, s13, 16
	s_max_u32 s84, s84, s13
	s_mov_b32 s85, 0
	s_mov_b32 s96, 0
	s_mov_b32 s87, s74
	s_mov_b32 s89, 0x07060302
	v_perm_b32 v132, v95, v6, s89
	v_perm_b32 v133, v93, v94, s89
	v_perm_b32 v134, v91, v92, s89
	v_perm_b32 v135, v89, v90, s89
	v_perm_b32 v136, v87, v88, s89
	v_perm_b32 v137, v85, v86, s89
	v_perm_b32 v138, v83, v84, s89
	v_perm_b32 v139, v81, v82, s89
	v_perm_b32 v140, v80, v4, s89
	v_perm_b32 v141, v78, v79, s89
	v_perm_b32 v142, v76, v77, s89
	v_perm_b32 v143, v74, v75, s89
	v_perm_b32 v144, v72, v73, s89
	v_perm_b32 v145, v70, v71, s89
	v_perm_b32 v146, v68, v69, s89
	v_perm_b32 v147, v66, v67, s89
	v_perm_b32 v148, v65, v2, s89
	v_perm_b32 v149, v49, v64, s89
	v_perm_b32 v150, v46, v48, s89
	v_perm_b32 v151, v34, v35, s89
	v_perm_b32 v152, v32, v33, s89
	v_perm_b32 v153, v30, v31, s89
	v_perm_b32 v154, v23, v28, s89
	v_perm_b32 v155, v21, v22, s89
	v_perm_b32 v156, v20, v0, s89
	v_perm_b32 v157, v18, v19, s89
	v_perm_b32 v158, v16, v17, s89
	v_perm_b32 v159, v14, v15, s89
	v_perm_b32 v160, v12, v13, s89
	v_perm_b32 v161, v10, v11, s89
	v_perm_b32 v162, v8, v9, s89
	v_perm_b32 v163, v3, v7, s89
	v_mov_b32_e32 v39, 0x10001
.Lbis_loop:
	s_lshl_b32 s12, 1, s75
	s_or_b32 s12, s85, s12
	s_lshr_b32 s13, s12, 16
	s_cmp_gt_u32 s13, s84
	s_cbranch_scc1 .Lbis_next
	v_mov_b32_e32 v24, s12
	v_mov_b32_e32 v25, 0
	s_cmp_lt_u32 s75, 16
	s_cbranch_scc1 .Lbis_full
	s_lshr_b32 s20, s12, 16
	s_sub_u32 s20, s20, 1
	s_mul_i32 s20, s20, 0x10001
	v_mov_b32_e32 v38, s20
	s_cmp_eq_u64 s[18:19], 0
	s_cbranch_scc1 .Lbis_pk_done
	v_pk_sub_u16 v26, v132, v38 clamp
	v_pk_sub_u16 v27, v133, v38 clamp
	v_pk_min_u16 v26, v26, v39
	v_pk_min_u16 v27, v27, v39
	v_pk_add_u16 v25, v25, v26
	v_pk_add_u16 v25, v25, v27
	v_pk_sub_u16 v26, v134, v38 clamp
	v_pk_sub_u16 v27, v135, v38 clamp
	v_pk_min_u16 v26, v26, v39
	v_pk_min_u16 v27, v27, v39
	v_pk_add_u16 v25, v25, v26
	v_pk_add_u16 v25, v25, v27
	v_pk_sub_u16 v26, v136, v38 clamp
	v_pk_sub_u16 v27, v137, v38 clamp
	v_pk_min_u16 v26, v26, v39
	v_pk_min_u16 v27, v27, v39
	v_pk_add_u16 v25, v25, v26
	v_pk_add_u16 v25, v25, v27
	v_pk_sub_u16 v26, v138, v38 clamp
	v_pk_sub_u16 v27, v139, v38 clamp
	v_pk_min_u16 v26, v26, v39
	v_pk_min_u16 v27, v27, v39
	v_pk_add_u16 v25, v25, v26
	v_pk_add_u16 v25, v25, v27
	s_cmp_eq_u64 s[16:17], 0
	s_cbranch_scc1 .Lbis_pk_done
	v_pk_sub_u16 v26, v140, v38 clamp
	v_pk_sub_u16 v27, v141, v38 clamp
	v_pk_min_u16 v26, v26, v39
	v_pk_min_u16 v27, v27, v39
	v_pk_add_u16 v25, v25, v26
	v_pk_add_u16 v25, v25, v27
	v_pk_sub_u16 v26, v142, v38 clamp
	v_pk_sub_u16 v27, v143, v38 clamp
	v_pk_min_u16 v26, v26, v39
	v_pk_min_u16 v27, v27, v39
	v_pk_add_u16 v25, v25, v26
	v_pk_add_u16 v25, v25, v27
	v_pk_sub_u16 v26, v144, v38 clamp
	v_pk_sub_u16 v27, v145, v38 clamp
	v_pk_min_u16 v26, v26, v39
	v_pk_min_u16 v27, v27, v39
	v_pk_add_u16 v25, v25, v26
	v_pk_add_u16 v25, v25, v27
	v_pk_sub_u16 v26, v146, v38 clamp
	v_pk_sub_u16 v27, v147, v38 clamp
	v_pk_min_u16 v26, v26, v39
	v_pk_min_u16 v27, v27, v39
	v_pk_add_u16 v25, v25, v26
	v_pk_add_u16 v25, v25, v27
	s_cmp_eq_u64 s[14:15], 0
	s_cbranch_scc1 .Lbis_pk_done
	v_pk_sub_u16 v26, v148, v38 clamp
	v_pk_sub_u16 v27, v149, v38 clamp
	v_pk_min_u16 v26, v26, v39
	v_pk_min_u16 v27, v27, v39
	v_pk_add_u16 v25, v25, v26
	v_pk_add_u16 v25, v25, v27
	v_pk_sub_u16 v26, v150, v38 clamp
	v_pk_sub_u16 v27, v151, v38 clamp
	v_pk_min_u16 v26, v26, v39
	v_pk_min_u16 v27, v27, v39
	v_pk_add_u16 v25, v25, v26
	v_pk_add_u16 v25, v25, v27
	v_pk_sub_u16 v26, v152, v38 clamp
	v_pk_sub_u16 v27, v153, v38 clamp
	v_pk_min_u16 v26, v26, v39
	v_pk_min_u16 v27, v27, v39
	v_pk_add_u16 v25, v25, v26
	v_pk_add_u16 v25, v25, v27
	v_pk_sub_u16 v26, v154, v38 clamp
	v_pk_sub_u16 v27, v155, v38 clamp
	v_pk_min_u16 v26, v26, v39
	v_pk_min_u16 v27, v27, v39
	v_pk_add_u16 v25, v25, v26
	v_pk_add_u16 v25, v25, v27
	s_cmp_eq_u64 vcc, 0
	s_cbranch_scc1 .Lbis_pk_done
	v_pk_sub_u16 v26, v156, v38 clamp
	v_pk_sub_u16 v27, v157, v38 clamp
	v_pk_min_u16 v26, v26, v39
	v_pk_min_u16 v27, v27, v39
	v_pk_add_u16 v25, v25, v26
	v_pk_add_u16 v25, v25, v27
	v_pk_sub_u16 v26, v158, v38 clamp
	v_pk_sub_u16 v27, v159, v38 clamp
	v_pk_min_u16 v26, v26, v39
	v_pk_min_u16 v27, v27, v39
	v_pk_add_u16 v25, v25, v26
	v_pk_add_u16 v25, v25, v27
	v_pk_sub_u16 v26, v160, v38 clamp
	v_pk_sub_u16 v27, v161, v38 clamp
	v_pk_min_u16 v26, v26, v39
	v_pk_min_u16 v27, v27, v39
	v_pk_add_u16 v25, v25, v26
	v_pk_add_u16 v25, v25, v27
	v_pk_sub_u16 v26, v162, v38 clamp
	v_pk_sub_u16 v27, v163, v38 clamp
	v_pk_min_u16 v26, v26, v39
	v_pk_min_u16 v27, v27, v39
	v_pk_add_u16 v25, v25, v26
	v_pk_add_u16 v25, v25, v27
.Lbis_pk_done:
	v_lshrrev_b32_e32 v26, 16, v25
	v_and_b32_e32 v25, 0xffff, v25
	v_add_u32_e32 v25, v25, v26
	s_branch .Lbis_cnt_done
	s_nop 0
	s_nop 0
	s_nop 0
	s_nop 0
	s_nop 0
	s_nop 0
	s_nop 0
	s_nop 0
; __device__ __forceinline__ void attn_item(const Ptrs& P, unsigned char* lds, int b, int tq0, int tid) {
;     ...
;             for (int k = 0; k < 4; ++k) if (16 * k < nact) {
; #pragma unroll
;                 for (int r = 16 * k; r < 16 * k + 16; ++r) cnt += (unsigned)__popcll(__ballot(k2[r] >= cand)); }
.Lbis_full:
	s_cmp_eq_u64 s[18:19], 0
	s_cbranch_scc1 .Lbis_cnt_done
	v_cmp_ge_u32_e64 s[78:79], v6, v24
	v_cmp_ge_u32_e64 s[90:91], v95, v24
	v_cmp_ge_u32_e64 s[92:93], v94, v24
	v_addc_co_u32_e64 v25, s[94:95], 0, v25, s[78:79]
	v_cmp_ge_u32_e64 s[78:79], v93, v24
	v_addc_co_u32_e64 v25, s[94:95], 0, v25, s[90:91]
	v_cmp_ge_u32_e64 s[90:91], v92, v24
	v_addc_co_u32_e64 v25, s[94:95], 0, v25, s[92:93]
	v_cmp_ge_u32_e64 s[92:93], v91, v24
	v_addc_co_u32_e64 v25, s[94:95], 0, v25, s[78:79]
	v_cmp_ge_u32_e64 s[78:79], v90, v24
	v_addc_co_u32_e64 v25, s[94:95], 0, v25, s[90:91]
	v_cmp_ge_u32_e64 s[90:91], v89, v24
	v_addc_co_u32_e64 v25, s[94:95], 0, v25, s[92:93]
	v_cmp_ge_u32_e64 s[92:93], v88, v24
	v_addc_co_u32_e64 v25, s[94:95], 0, v25, s[78:79]
	v_cmp_ge_u32_e64 s[78:79], v87, v24
	v_addc_co_u32_e64 v25, s[94:95], 0, v25, s[90:91]
	v_cmp_ge_u32_e64 s[90:91], v86, v24
	v_addc_co_u32_e64 v25, s[94:95], 0, v25, s[92:93]
	v_cmp_ge_u32_e64 s[92:93], v85, v24
	v_addc_co_u32_e64 v25, s[94:95], 0, v25, s[78:79]
	v_cmp_ge_u32_e64 s[78:79], v84, v24
	v_addc_co_u32_e64 v25, s[94:95], 0, v25, s[90:91]
	v_cmp_ge_u32_e64 s[90:91], v83, v24
	v_addc_co_u32_e64 v25, s[94:95], 0, v25, s[92:93]
	v_cmp_ge_u32_e64 s[92:93], v82, v24
	v_addc_co_u32_e64 v25, s[94:95], 0, v25, s[78:79]
	v_cmp_ge_u32_e64 s[78:79], v81, v24
	v_addc_co_u32_e64 v25, s[94:95], 0, v25, s[90:91]
	v_addc_co_u32_e64 v25, s[94:95], 0, v25, s[92:93]
	v_addc_co_u32_e64 v25, s[94:95], 0, v25, s[78:79]
	s_cmp_eq_u64 s[16:17], 0
	s_cbranch_scc1 .Lbis_cnt_done
	v_cmp_ge_u32_e64 s[78:79], v4, v24
	v_cmp_ge_u32_e64 s[90:91], v80, v24
	v_cmp_ge_u32_e64 s[92:93], v79, v24
	v_addc_co_u32_e64 v25, s[94:95], 0, v25, s[78:79]
	v_cmp_ge_u32_e64 s[78:79], v78, v24
	v_addc_co_u32_e64 v25, s[94:95], 0, v25, s[90:91]
	v_cmp_ge_u32_e64 s[90:91], v77, v24
	v_addc_co_u32_e64 v25, s[94:95], 0, v25, s[92:93]
	v_cmp_ge_u32_e64 s[92:93], v76, v24
	v_addc_co_u32_e64 v25, s[94:95], 0, v25, s[78:79]
	v_cmp_ge_u32_e64 s[78:79], v75, v24
	v_addc_co_u32_e64 v25, s[94:95], 0, v25, s[90:91]
	v_cmp_ge_u32_e64 s[90:91], v74, v24
	v_addc_co_u32_e64 v25, s[94:95], 0, v25, s[92:93]
	v_cmp_ge_u32_e64 s[92:93], v73, v24
	v_addc_co_u32_e64 v25, s[94:95], 0, v25, s[78:79]
	v_cmp_ge_u32_e64 s[78:79], v72, v24
	v_addc_co_u32_e64 v25, s[94:95], 0, v25, s[90:91]
	v_cmp_ge_u32_e64 s[90:91], v71, v24
	v_addc_co_u32_e64 v25, s[94:95], 0, v25, s[92:93]
	v_cmp_ge_u32_e64 s[92:93], v70, v24
	v_addc_co_u32_e64 v25, s[94:95], 0, v25, s[78:79]
	v_cmp_ge_u32_e64 s[78:79], v69, v24
	v_addc_co_u32_e64 v25, s[94:95], 0, v25, s[90:91]
	v_cmp_ge_u32_e64 s[90:91], v68, v24
	v_addc_co_u32_e64 v25, s[94:95], 0, v25, s[92:93]
	v_cmp_ge_u32_e64 s[92:93], v67, v24
	v_addc_co_u32_e64 v25, s[94:95], 0, v25, s[78:79]
	v_cmp_ge_u32_e64 s[78:79], v66, v24
	v_addc_co_u32_e64 v25, s[94:95], 0, v25, s[90:91]
	v_addc_co_u32_e64 v25, s[94:95], 0, v25, s[92:93]
	v_addc_co_u32_e64 v25, s[94:95], 0, v25, s[78:79]
	s_cmp_eq_u64 s[14:15], 0
	s_cbranch_scc1 .Lbis_cnt_done
	v_cmp_ge_u32_e64 s[78:79], v2, v24
	v_cmp_ge_u32_e64 s[90:91], v65, v24
	v_cmp_ge_u32_e64 s[92:93], v64, v24
	v_addc_co_u32_e64 v25, s[94:95], 0, v25, s[78:79]
	v_cmp_ge_u32_e64 s[78:79], v49, v24
	v_addc_co_u32_e64 v25, s[94:95], 0, v25, s[90:91]
	v_cmp_ge_u32_e64 s[90:91], v48, v24
	v_addc_co_u32_e64 v25, s[94:95], 0, v25, s[92:93]
	v_cmp_ge_u32_e64 s[92:93], v46, v24
	v_addc_co_u32_e64 v25, s[94:95], 0, v25, s[78:79]
	v_cmp_ge_u32_e64 s[78:79], v35, v24
	v_addc_co_u32_e64 v25, s[94:95], 0, v25, s[90:91]
	v_cmp_ge_u32_e64 s[90:91], v34, v24
	v_addc_co_u32_e64 v25, s[94:95], 0, v25, s[92:93]
	v_cmp_ge_u32_e64 s[92:93], v33, v24
	v_addc_co_u32_e64 v25, s[94:95], 0, v25, s[78:79]
	v_cmp_ge_u32_e64 s[78:79], v32, v24
	v_addc_co_u32_e64 v25, s[94:95], 0, v25, s[90:91]
	v_cmp_ge_u32_e64 s[90:91], v31, v24
	v_addc_co_u32_e64 v25, s[94:95], 0, v25, s[92:93]
	v_cmp_ge_u32_e64 s[92:93], v30, v24
	v_addc_co_u32_e64 v25, s[94:95], 0, v25, s[78:79]
	v_cmp_ge_u32_e64 s[78:79], v28, v24
	v_addc_co_u32_e64 v25, s[94:95], 0, v25, s[90:91]
	v_cmp_ge_u32_e64 s[90:91], v23, v24
	v_addc_co_u32_e64 v25, s[94:95], 0, v25, s[92:93]
	v_cmp_ge_u32_e64 s[92:93], v22, v24
	v_addc_co_u32_e64 v25, s[94:95], 0, v25, s[78:79]
	v_cmp_ge_u32_e64 s[78:79], v21, v24
	v_addc_co_u32_e64 v25, s[94:95], 0, v25, s[90:91]
	v_addc_co_u32_e64 v25, s[94:95], 0, v25, s[92:93]
	v_addc_co_u32_e64 v25, s[94:95], 0, v25, s[78:79]
	s_cmp_eq_u64 vcc, 0
	s_cbranch_scc1 .Lbis_cnt_done
	v_cmp_ge_u32_e64 s[78:79], v0, v24
	v_cmp_ge_u32_e64 s[90:91], v20, v24
	v_cmp_ge_u32_e64 s[92:93], v19, v24
	v_addc_co_u32_e64 v25, s[94:95], 0, v25, s[78:79]
	v_cmp_ge_u32_e64 s[78:79], v18, v24
	v_addc_co_u32_e64 v25, s[94:95], 0, v25, s[90:91]
	v_cmp_ge_u32_e64 s[90:91], v17, v24
	v_addc_co_u32_e64 v25, s[94:95], 0, v25, s[92:93]
	v_cmp_ge_u32_e64 s[92:93], v16, v24
	v_addc_co_u32_e64 v25, s[94:95], 0, v25, s[78:79]
	v_cmp_ge_u32_e64 s[78:79], v15, v24
	v_addc_co_u32_e64 v25, s[94:95], 0, v25, s[90:91]
	v_cmp_ge_u32_e64 s[90:91], v14, v24
	v_addc_co_u32_e64 v25, s[94:95], 0, v25, s[92:93]
	v_cmp_ge_u32_e64 s[92:93], v13, v24
	v_addc_co_u32_e64 v25, s[94:95], 0, v25, s[78:79]
	v_cmp_ge_u32_e64 s[78:79], v12, v24
	v_addc_co_u32_e64 v25, s[94:95], 0, v25, s[90:91]
	v_cmp_ge_u32_e64 s[90:91], v11, v24
	v_addc_co_u32_e64 v25, s[94:95], 0, v25, s[92:93]
	v_cmp_ge_u32_e64 s[92:93], v10, v24
	v_addc_co_u32_e64 v25, s[94:95], 0, v25, s[78:79]
	v_cmp_ge_u32_e64 s[78:79], v9, v24
	v_addc_co_u32_e64 v25, s[94:95], 0, v25, s[90:91]
	v_cmp_ge_u32_e64 s[90:91], v8, v24
	v_addc_co_u32_e64 v25, s[94:95], 0, v25, s[92:93]
	v_cmp_ge_u32_e64 s[92:93], v7, v24
	v_addc_co_u32_e64 v25, s[94:95], 0, v25, s[78:79]
	v_cmp_ge_u32_e64 s[78:79], v3, v24
	v_addc_co_u32_e64 v25, s[94:95], 0, v25, s[90:91]
	v_addc_co_u32_e64 v25, s[94:95], 0, v25, s[92:93]
	v_addc_co_u32_e64 v25, s[94:95], 0, v25, s[78:79]
